# attention S^T = K.Q^T: K fragments read two steps ahead of their MFMAs (three register buffers) instead of read-wait-use
# speedup vs baseline: 1.0073x; 1.0026x over previous
; template <int NF, int RB>
; __device__ __forceinline__ void qkt(f32x16& p0, f32x16& p1, const char* Kt, int r32, int hi, const bf16x8* qr, float init) {
; #pragma unroll
;     for (int r = 0; r < 16; ++r) { p0[r] = init; p1[r] = init; }
;     const char* kb[4];
; #pragma unroll
;     for (int dd = 0; dd < 4; ++dd) kb[dd] = Kt + r32 * RB + (((dd * 16 + hi * 8) * 2) ^ ((r32 & 7) << 4));
; #pragma unroll
;     for (int d0 = 0; d0 < NF; ++d0) { const char* a = kb[d0 & 3] + (d0 >> 2) * 128;
;         bf16x8 b0 = *reinterpret_cast<const bf16x8*>(a);
;         bf16x8 b1 = *reinterpret_cast<const bf16x8*>(a + 32 * RB);
;         p0 = __builtin_amdgcn_mfma_f32_32x32x16_bf16(b0, qr[d0], p0, 0, 0, 0);
;         p1 = __builtin_amdgcn_mfma_f32_32x32x16_bf16(b1, qr[d0], p1, 0, 0, 0); }
; }
; __device__ __forceinline__ void attn_block(const bf16_t* __restrict__ proj, bf16_t* __restrict__ mixed, int b, int h, int qb, char* lds) {
;     ...
;             f32x16 p0, p1; const int dq = qm - kb;
;             qkt<8, 256>(p0, p1, K_lds + buf * SHM, r32, hi, qr, -slr * (float)dq);
.LBB0_312:
	s_cmp_gt_i32 s89, s78
	s_cbranch_scc1 .LBB0_316
	v_add_u32_e32 v0, s65, v232
	v_cvt_f32_i32_e32 v2, v0
	s_lshl_b32 s56, s56, 14
	s_mov_b64 s[96:97], -1
	s_cmpk_lt_i32 s65, 0x240
	v_mul_f32_e64 v80, -v203, v2
	v_add_u32_e32 v2, s56, v213
	v_add_u32_e32 v10, v2, v214
	v_add_u32_e32 v11, v2, v215
	v_add_u32_e32 v12, v2, v216
	v_add_u32_e32 v13, v2, v217
	ds_read_b128 v[2:5], v10 offset:32768
	ds_read_b128 v[6:9], v10 offset:40960
	ds_read_b128 v[236:239], v11 offset:32768
	ds_read_b128 v[240:243], v11 offset:40960
	ds_read_b128 v[246:249], v12 offset:32768
	ds_read_b128 v[250:253], v12 offset:40960
	v_mov_b32_e32 v81, v80
	v_mov_b32_e32 v82, v80
	v_mov_b32_e32 v83, v80
	v_mov_b32_e32 v84, v80
	v_mov_b32_e32 v85, v80
	v_mov_b32_e32 v86, v80
	v_mov_b32_e32 v87, v80
	v_mov_b32_e32 v88, v80
	v_mov_b32_e32 v89, v80
	v_mov_b32_e32 v90, v80
	v_mov_b32_e32 v91, v80
	v_mov_b32_e32 v92, v80
	v_mov_b32_e32 v93, v80
	v_mov_b32_e32 v94, v80
	v_mov_b32_e32 v95, v80
	s_waitcnt lgkmcnt(4)
	s_nop 0
	v_mfma_f32_32x32x16_bf16 v[96:111], v[2:5], v[144:147], v[80:95]
	v_mfma_f32_32x32x16_bf16 v[80:95], v[6:9], v[144:147], v[80:95]
	ds_read_b128 v[2:5], v13 offset:32768
	ds_read_b128 v[6:9], v13 offset:40960
	s_waitcnt lgkmcnt(4)
	v_mfma_f32_32x32x16_bf16 v[96:111], v[236:239], v[148:151], v[96:111]
	v_mfma_f32_32x32x16_bf16 v[80:95], v[240:243], v[148:151], v[80:95]
	ds_read_b128 v[236:239], v10 offset:32896
	ds_read_b128 v[240:243], v10 offset:41088
	s_waitcnt lgkmcnt(4)
	v_mfma_f32_32x32x16_bf16 v[96:111], v[246:249], v[152:155], v[96:111]
	v_mfma_f32_32x32x16_bf16 v[80:95], v[250:253], v[152:155], v[80:95]
	ds_read_b128 v[246:249], v11 offset:32896
	ds_read_b128 v[250:253], v11 offset:41088
	s_waitcnt lgkmcnt(4)
	v_mfma_f32_32x32x16_bf16 v[96:111], v[2:5], v[156:159], v[96:111]
	v_mfma_f32_32x32x16_bf16 v[80:95], v[6:9], v[156:159], v[80:95]
	ds_read_b128 v[2:5], v12 offset:32896
	ds_read_b128 v[6:9], v12 offset:41088
	s_waitcnt lgkmcnt(4)
	v_mfma_f32_32x32x16_bf16 v[96:111], v[236:239], v[160:163], v[96:111]
	v_mfma_f32_32x32x16_bf16 v[80:95], v[240:243], v[160:163], v[80:95]
	ds_read_b128 v[236:239], v13 offset:32896
	ds_read_b128 v[240:243], v13 offset:41088
	s_waitcnt lgkmcnt(4)
	v_mfma_f32_32x32x16_bf16 v[96:111], v[246:249], v[164:167], v[96:111]
	v_mfma_f32_32x32x16_bf16 v[80:95], v[250:253], v[164:167], v[80:95]
	s_waitcnt lgkmcnt(2)
	v_mfma_f32_32x32x16_bf16 v[96:111], v[2:5], v[168:171], v[96:111]
	v_mfma_f32_32x32x16_bf16 v[80:95], v[6:9], v[168:171], v[80:95]
	s_waitcnt lgkmcnt(0)
	v_mfma_f32_32x32x16_bf16 v[96:111], v[236:239], v[172:175], v[96:111]
	v_mfma_f32_32x32x16_bf16 v[80:95], v[240:243], v[172:175], v[80:95]
	s_cbranch_scc1 .LBB0_317
	s_and_b64 vcc, exec, s[96:97]
	s_cbranch_vccnz .LBB0_334
